# attention loop: last 4 exps of each P.V half-step moved into the following Q.K half-step (VALU balance)
# speedup vs baseline: 1.0045x; 1.0045x over previous
; #define WAIT_BAR(N) asm volatile("s_waitcnt vmcnt(" #N ") lgkmcnt(0)\n\ts_barrier":::"memory")
;   #define DMA_K(t,slot) glds16(ksrc+(long)(t)*KVBLK*KP,(unsigned)__builtin_amdgcn_readfirstlane(kdst+(slot)))
;   #define DMA_V(t,slot) glds16(vsrc+(long)(t)*KVBLK*KP,(unsigned)__builtin_amdgcn_readfirstlane(vdst+(slot)))
;   #define START(P0,P1) do{ _Pragma("unroll") for(int r=0;r<16;++r)P0[r]=__builtin_amdgcn_exp2f(P0[r]); }while(0)
; template<int THRL> __device__ __forceinline__ void attn_unit(int b,int h,int qb,const bf16*Q,const bf16*__restrict__ K,const bf16*__restrict__ V,bf16*O,char*shm,float m2){
;   const int tid=threadIdx.x,lane=tid&63,r32=lane&31,hi=lane>>5; const int wid=__builtin_amdgcn_readfirstlane(tid>>6);
;   const long rowbase=(long)b*SEQ; const int q0=qb*QB; const int kvh=h>>2;
;   const bf16*Qw=Q+(rowbase+q0+wid*QBLK)*QP+h*D;
;   const bf16*Kh=K+rowbase*KP+kvh*D,*Vh=V+rowbase*KP+kvh*D;
;   const unsigned lds0=(unsigned)(uintptr_t)shm;
;   float*wsf=(float*)(shm+LDS_WS)+wid*64;
;   const bf16*ksrc=Kh+(long)lane*KP+wid*8;
;   const bf16*vsrc=Vh+(long)(16*(wid&3)+(lane>>2))*KP+(wid>>2)*32+(lane&3)*8;
;   const unsigned kdst=lds0+LDS_K+wid*1024, vdst=lds0+LDS_V+wid*1024;
;     ...
;   const int vb0=(int)(lds0+LDS_V)+((lane>>4)&1)*32+(lane&3)*8+(4*hi+((lane&15)>>2))*64;
;   const char*Kbase=shm+LDS_K; bf16x8 kf[8];
;   const lds_cptr shm3=(lds_cptr)shm; const lds_cptr kp0=shm3+LDS_K+hi*1024+r32*16; const lds_cptr vp0=shm3+LDS_V+((lane>>4)&1)*32+(lane&3)*8+(4*hi+((lane&15)>>2))*64;
;   constexpr int NT=SEQ/KVBLK;
;   if(wid>=4)__builtin_amdgcn_s_setprio(1);
;   DMA_K(0,0);DMA_V(0,0);DMA_K(1,SLOTB);
;   bf16x8 qr[4];
;   #pragma unroll
;   for(int d0=0;d0<4;++d0)qr[d0]=*reinterpret_cast<const bf16x8*>(&Qw[(long)r32*QP+d0*16+hi*8]);
;   float l_reg=0.f;f32x16 o[2];o[0]=f32x16{};o[1]=f32x16{};f32x16 negm;
;   _Pragma("unroll") for(int r=0;r<16;++r)negm[r]=-m2;
;   asm volatile("":"+v"(negm));
;     ...
;   f32x16 pA0,pA1,pB0,pB1;
;   int sl_prev=0,sl_cur=0,sl_next=SLOTB;
;     ...
;   DMA_K(2,2*SLOTB);
;   WAIT_BAR(3);
;   qkt(pA0,pA1,Kbase,qr,negm,r32,hi);asm volatile("s_nop 15\n\ts_nop 7":"+v"(pA0),"+v"(pA1));
;   START(pA0,pA1);
;   _Pragma("unroll") for(int r=0;r<16;++r)pA1[r]=__builtin_amdgcn_exp2f(pA1[r]);
;   WAIT_BAR(0);
;   DMA_K(3,0);DMA_V(1,SLOTB);
;   ROT();
;   kload8(kf,kp0+sl_cur);
;   WAIT_BAR(2);
.LBB0_828:
	s_lshl_b32 s0, s0, 8
	s_lshr_b32 s9, s13, 6
	s_and_b32 s0, s0, 0x1f00
	s_or_b32 s0, s10, s0
	s_lshl_b32 s4, s9, 5
	s_add_u32 s4, s0, s4
	s_addc_u32 s5, s11, 0
	s_lshl_b64 s[4:5], s[4:5], 10
	s_add_u32 s54, s7, s4
	s_addc_u32 s55, s8, s5
	s_lshl_b32 s0, s9, 4
	s_lshr_b32 s18, s13, 2
	v_lshl_add_u64 v[212:213], v[192:193], 0, s[0:1]
	v_and_or_b32 v18, s18, 48, v218
	s_and_b32 s0, s18, 0x3fffffc0
	s_lshl_b32 s5, s9, 10
	v_lshlrev_b32_e32 v190, 8, v18
	s_cmp_lg_u32 0, -1
	v_lshl_add_u64 v[18:19], s[40:41], 0, v[190:191]
	s_cselect_b32 s4, 0, 0
	v_lshl_add_u64 v[18:19], v[18:19], 0, s[0:1]
	v_mov_b32_e32 v199, v191
	s_add_i32 s12, s5, s4
	s_mov_b32 s14, m0
	s_mov_b32 m0, s12
	s_nop 0
	global_load_lds_dwordx4 v[212:213], off
	s_mov_b32 m0, s14
	v_lshl_add_u64 v[210:211], v[18:19], 0, v[198:199]
	s_add_i32 s4, s12, 0x6000
	s_mov_b32 s14, m0
	s_mov_b32 m0, s4
	s_nop 0
	global_load_lds_dwordx4 v[210:211], off
	s_mov_b32 m0, s14
	v_lshl_add_u64 v[18:19], v[212:213], 0, s[42:43]
	s_add_i32 s14, s12, 0x2000
	s_mov_b32 s15, m0
	s_mov_b32 m0, s14
	s_nop 0
	global_load_lds_dwordx4 v[18:19], off
	s_mov_b32 m0, s15
	global_load_dwordx4 v[174:177], v229, s[54:55]
	global_load_dwordx4 v[170:173], v229, s[54:55] offset:32
	global_load_dwordx4 v[162:165], v229, s[54:55] offset:64
	global_load_dwordx4 v[154:157], v229, s[54:55] offset:96
	v_mov_b64_e32 v[64:65], v[16:17]
	v_mov_b64_e32 v[62:63], v[14:15]
	v_mov_b64_e32 v[60:61], v[12:13]
	v_mov_b64_e32 v[58:59], v[10:11]
	v_mov_b64_e32 v[56:57], v[8:9]
	v_mov_b64_e32 v[54:55], v[6:7]
	v_mov_b64_e32 v[52:53], v[4:5]
	v_mov_b64_e32 v[50:51], v[2:3]
	v_lshl_add_u64 v[18:19], v[212:213], 0, s[46:47]
	s_add_i32 s14, s12, 0x4000
	s_mov_b32 s15, m0
	s_mov_b32 m0, s14
	s_nop 0
	global_load_lds_dwordx4 v[18:19], off
	s_mov_b32 m0, s15
	s_waitcnt vmcnt(3) lgkmcnt(0)
	s_barrier
	ds_read_b128 v[18:21], v219
	ds_read_b128 v[22:25], v219 offset:512
	s_mov_b32 s19, s1
	s_and_b32 s18, s18, 0x3ffffff0
	s_lshl_b32 s20, s13, 6
	v_lshl_add_u64 v[214:215], v[194:195], 0, s[18:19]
	s_and_b32 s18, s20, 0x3000
	v_lshl_or_b32 v190, v228, 1, s18
	v_lshl_add_u64 v[48:49], v[212:213], 0, s[48:49]
	s_add_i32 s19, s12, 0x8000
	v_lshl_add_u64 v[98:99], v[210:211], 0, s[42:43]
	v_mov_b32_e32 v199, 0
	s_mov_b32 s14, -1
	s_mov_b32 s17, 0
	s_movk_i32 s16, 0x2000
	s_movk_i32 s15, 0x4000
	v_mov_b32_e32 v26, v199
	v_mov_b32_e32 v27, v199
	s_waitcnt vmcnt(3) lgkmcnt(1)
	v_mfma_f32_32x32x16_bf16 v[66:81], v[18:21], v[174:177], v[50:65]
	s_waitcnt lgkmcnt(0)
	v_mfma_f32_32x32x16_bf16 v[32:47], v[22:25], v[174:177], v[50:65]
	ds_read_b128 v[18:21], v219 offset:2048
	ds_read_b128 v[22:25], v219 offset:2560
	ds_read_b128 v[28:31], v219 offset:4608
	ds_read_b128 v[82:85], v219 offset:4096
	s_waitcnt vmcnt(2) lgkmcnt(3)
	v_mfma_f32_32x32x16_bf16 v[66:81], v[18:21], v[170:173], v[66:81]
	v_mov_b32_e32 v18, 0
	v_mov_b32_e32 v19, v199
	v_mov_b32_e32 v20, v199
	v_mov_b32_e32 v21, v199
	s_waitcnt lgkmcnt(2)
	v_mfma_f32_32x32x16_bf16 v[32:47], v[22:25], v[170:173], v[32:47]
	v_mov_b32_e32 v22, v199
	v_mov_b32_e32 v23, v199
	v_mov_b32_e32 v24, v199
	v_mov_b32_e32 v25, v199
	s_waitcnt vmcnt(1) lgkmcnt(0)
	v_mfma_f32_32x32x16_bf16 v[66:81], v[82:85], v[162:165], v[66:81]
	ds_read_b128 v[82:85], v219 offset:6656
	ds_read_b128 v[86:89], v219 offset:6144
	v_mfma_f32_32x32x16_bf16 v[32:47], v[28:31], v[162:165], v[32:47]
	v_mov_b32_e32 v28, v199
	v_mov_b32_e32 v29, v199
	v_mov_b32_e32 v30, v199
	v_mov_b32_e32 v31, v199
	s_waitcnt vmcnt(0) lgkmcnt(0)
	v_mfma_f32_32x32x16_bf16 v[66:81], v[86:89], v[154:157], v[66:81]
	v_lshl_add_u64 v[86:87], s[0:1], 0, v[190:191]
	v_lshl_add_u64 v[216:217], v[196:197], 0, v[86:87]
	v_mfma_f32_32x32x16_bf16 v[32:47], v[82:85], v[154:157], v[32:47]
	s_nop 15
	s_nop 7
	s_waitcnt vmcnt(0) lgkmcnt(0)
	s_barrier
	s_mov_b32 s0, m0
	s_mov_b32 m0, s12
	s_nop 0
	global_load_lds_dwordx4 v[48:49], off
	s_mov_b32 m0, s0
	v_mov_b32_e32 v48, v199
	s_mov_b32 s0, m0
	s_mov_b32 m0, s19
	s_nop 0
	global_load_lds_dwordx4 v[98:99], off
	s_mov_b32 m0, s0
	ds_read_b128 v[98:101], v219 offset:8192
	ds_read_b128 v[182:185], v219 offset:8704
	ds_read_b128 v[186:189], v219 offset:10240
	ds_read_b128 v[178:181], v219 offset:10752
	ds_read_b128 v[142:145], v219 offset:12288
	ds_read_b128 v[138:141], v219 offset:12800
	ds_read_b128 v[134:137], v219 offset:14336
	ds_read_b128 v[130:133], v219 offset:14848
	v_exp_f32_e32 v82, v66
	v_exp_f32_e32 v83, v67
	v_exp_f32_e32 v84, v68
	v_exp_f32_e32 v85, v69
	v_exp_f32_e32 v86, v70
	v_exp_f32_e32 v87, v71
	v_exp_f32_e32 v88, v72
	v_exp_f32_e32 v89, v73
	v_exp_f32_e32 v90, v74
	v_exp_f32_e32 v91, v75
	v_exp_f32_e32 v92, v76
	v_exp_f32_e32 v93, v77
	v_exp_f32_e32 v94, v78
	v_exp_f32_e32 v95, v79
	v_exp_f32_e32 v96, v80
	v_exp_f32_e32 v97, v81
	v_exp_f32_e32 v66, v32
	v_exp_f32_e32 v67, v33
	v_exp_f32_e32 v68, v34
	v_exp_f32_e32 v69, v35
	v_exp_f32_e32 v70, v36
	v_exp_f32_e32 v71, v37
	v_exp_f32_e32 v72, v38
	v_exp_f32_e32 v73, v39
	v_exp_f32_e32 v74, v40
	v_exp_f32_e32 v75, v41
	v_exp_f32_e32 v76, v42
	v_exp_f32_e32 v77, v43
	v_mov_b32_e32 v78, v44
	v_mov_b32_e32 v79, v45
	v_mov_b32_e32 v80, v46
	v_mov_b32_e32 v81, v47
	s_waitcnt vmcnt(2) lgkmcnt(0)
	s_barrier
	v_mov_b32_e32 v32, v199
	v_mov_b32_e32 v33, v199
	v_mov_b32_e32 v34, 0
	v_mov_b32_e32 v35, v199
	v_mov_b32_e32 v36, v199
	v_mov_b32_e32 v37, v199
	v_mov_b32_e32 v38, v199
	v_mov_b32_e32 v39, v199
	v_mov_b32_e32 v40, v199
	v_mov_b32_e32 v41, v199
	v_mov_b32_e32 v42, v199
	v_mov_b32_e32 v43, v199
	v_mov_b32_e32 v44, v199
	v_mov_b32_e32 v45, v199
	v_mov_b32_e32 v46, v199
	v_mov_b32_e32 v47, v199
	v_mov_b32_e32 v49, v199
; #define WAIT_BAR(N) asm volatile("s_waitcnt vmcnt(" #N ") lgkmcnt(0)\n\ts_barrier":::"memory")
;   #define RESC() do{}while(0)
;   #define ROT() do{sl_prev=sl_cur;sl_cur=sl_next;sl_next=(sl_next==(NSLOT-1)*SLOTB)?0:sl_next+SLOTB;}while(0)
; template<int THRL> __device__ __forceinline__ void attn_unit(int b,int h,int qb,const bf16*Q,const bf16*__restrict__ K,const bf16*__restrict__ V,bf16*O,char*shm,float m2){
;     ...
;   int t=1;
;   for(;t+5<NT;t+=2){
;     STEP(pB0,pB1,pA0,pA1,t,true,true,true);     WAIT_BAR(2); RESC(); ROT();
;     STEP(pA0,pA1,pB0,pB1,t+1,true,true,true);   WAIT_BAR(2); RESC(); ROT();
;   }
.LBB0_829:
	v_add_u32_e32 v190, s17, v220
	ds_read_b64_tr_b16 v[230:231], v190 offset:24576
	ds_read_b64_tr_b16 v[232:233], v190 offset:25088
	v_add_f32_e32 v102, v82, v83
	v_add_f32_e32 v102, v84, v102
	v_add_f32_e32 v102, v85, v102
	v_add_f32_e32 v102, v86, v102
	v_add_f32_e32 v102, v87, v102
	v_cvt_pk_bf16_f32 v166, v82, v83
	v_cvt_pk_bf16_f32 v167, v84, v85
	s_waitcnt lgkmcnt(9)
	v_mfma_f32_32x32x16_bf16 v[114:129], v[98:101], v[174:177], v[50:65]
	v_exp_f32_e32 v78, v78
	ds_read_b64_tr_b16 v[82:83], v190 offset:28672
	ds_read_b64_tr_b16 v[84:85], v190 offset:29184
	v_add_f32_e32 v98, v88, v102
	v_add_f32_e32 v98, v89, v98
	v_add_f32_e32 v98, v90, v98
	v_add_f32_e32 v146, v91, v98
	s_waitcnt lgkmcnt(10)
	v_mfma_f32_32x32x16_bf16 v[98:113], v[182:185], v[174:177], v[50:65]
	v_exp_f32_e32 v79, v79
	v_cvt_pk_bf16_f32 v168, v86, v87
	v_cvt_pk_bf16_f32 v169, v88, v89
	ds_read_b64_tr_b16 v[86:87], v190 offset:25600
	ds_read_b64_tr_b16 v[88:89], v190 offset:26112
	v_add_f32_e32 v146, v92, v146
	v_add_f32_e32 v146, v93, v146
	v_add_f32_e32 v146, v94, v146
	v_add_f32_e32 v146, v95, v146
	v_cvt_pk_bf16_f32 v158, v90, v91
	v_cvt_pk_bf16_f32 v159, v92, v93
	s_waitcnt lgkmcnt(11)
	v_mfma_f32_32x32x16_bf16 v[114:129], v[186:189], v[170:173], v[114:129]
	v_exp_f32_e32 v80, v80
	ds_read_b64_tr_b16 v[90:91], v190 offset:29696
	ds_read_b64_tr_b16 v[92:93], v190 offset:30208
	s_waitcnt lgkmcnt(12)
	v_mfma_f32_32x32x16_bf16 v[98:113], v[178:181], v[170:173], v[98:113]
	v_exp_f32_e32 v81, v81
	v_add_f32_e32 v146, v96, v146
	v_add_f32_e32 v146, v97, v146
	v_add_f32_e32 v146, v66, v146
	v_add_f32_e32 v146, v67, v146
	v_cvt_pk_bf16_f32 v160, v94, v95
	v_cvt_pk_bf16_f32 v161, v96, v97
	ds_read_b64_tr_b16 v[94:95], v190 offset:26624
	ds_read_b64_tr_b16 v[96:97], v190 offset:27136
	s_waitcnt lgkmcnt(13)
	v_mfma_f32_32x32x16_bf16 v[114:129], v[142:145], v[162:165], v[114:129]
	v_add_f32_e32 v142, v68, v146
	v_add_f32_e32 v142, v69, v142
	v_add_f32_e32 v142, v70, v142
	v_add_f32_e32 v142, v71, v142
	v_cvt_pk_bf16_f32 v150, v66, v67
	v_cvt_pk_bf16_f32 v151, v68, v69
	ds_read_b64_tr_b16 v[66:67], v190 offset:30720
	ds_read_b64_tr_b16 v[68:69], v190 offset:31232
	s_waitcnt lgkmcnt(14)
	v_mfma_f32_32x32x16_bf16 v[98:113], v[138:141], v[162:165], v[98:113]
	v_add_f32_e32 v138, v72, v142
	v_add_f32_e32 v138, v73, v138
	v_add_f32_e32 v138, v74, v138
	v_add_f32_e32 v138, v75, v138
	v_cvt_pk_bf16_f32 v152, v70, v71
	v_cvt_pk_bf16_f32 v153, v72, v73
	ds_read_b64_tr_b16 v[70:71], v190 offset:27648
	ds_read_b64_tr_b16 v[72:73], v190 offset:28160
	s_waitcnt lgkmcnt(14)
	v_mfma_f32_32x32x16_bf16 v[114:129], v[134:137], v[154:157], v[114:129]
	v_add_f32_e32 v134, v76, v138
	v_add_f32_e32 v134, v77, v134
	v_add_f32_e32 v134, v78, v134
	v_add_f32_e32 v134, v79, v134
	v_cvt_pk_bf16_f32 v146, v74, v75
	v_cvt_pk_bf16_f32 v147, v76, v77
	ds_read_b64_tr_b16 v[74:75], v190 offset:31744
	ds_read_b64_tr_b16 v[76:77], v190 offset:32256
	v_mfma_f32_32x32x16_bf16 v[98:113], v[130:133], v[154:157], v[98:113]
	v_add_f32_e32 v130, v80, v134
	v_add_f32_e32 v130, v81, v130
	v_add_f32_e32 v130, 0, v130
	v_cvt_pk_bf16_f32 v148, v78, v79
	v_cvt_pk_bf16_f32 v149, v80, v81
	v_lshl_add_u64 v[78:79], v[214:215], 0, s[48:49]
	s_add_i32 s0, s16, s12
	s_mov_b32 s17, m0
	s_mov_b32 m0, s0
	s_nop 0
	global_load_lds_dwordx4 v[78:79], off
	s_mov_b32 m0, s17
	v_lshl_add_u64 v[78:79], v[216:217], 0, s[42:43]
	s_add_i32 s0, s15, s4
	s_mov_b32 s17, m0
	s_mov_b32 m0, s0
	s_nop 0
	global_load_lds_dwordx4 v[78:79], off
	s_mov_b32 m0, s17
	v_add_f32_e32 v190, v199, v130
	s_waitcnt lgkmcnt(14)
	v_mfma_f32_32x32x16_bf16 v[18:33], v[166:169], v[230:233], v[18:33]
	v_exp_f32_e32 v114, v114
	v_exp_f32_e32 v115, v115
	v_exp_f32_e32 v116, v116
	v_exp_f32_e32 v117, v117
	s_waitcnt lgkmcnt(12)
	v_mfma_f32_32x32x16_bf16 v[34:49], v[166:169], v[82:85], v[34:49]
	v_exp_f32_e32 v118, v118
	v_exp_f32_e32 v119, v119
	v_exp_f32_e32 v120, v120
	v_exp_f32_e32 v121, v121
	v_add_u32_e32 v82, s15, v219
	ds_read_b128 v[78:81], v82
	ds_read_b128 v[134:137], v82 offset:512
	s_waitcnt lgkmcnt(12)
	v_mfma_f32_32x32x16_bf16 v[18:33], v[158:161], v[86:89], v[18:33]
	v_exp_f32_e32 v122, v122
	v_exp_f32_e32 v123, v123
	v_exp_f32_e32 v124, v124
	v_exp_f32_e32 v125, v125
	ds_read_b128 v[138:141], v82 offset:2048
	ds_read_b128 v[142:145], v82 offset:2560
	s_waitcnt lgkmcnt(12)
	v_mfma_f32_32x32x16_bf16 v[34:49], v[158:161], v[90:93], v[34:49]
	v_exp_f32_e32 v126, v126
	v_exp_f32_e32 v127, v127
	v_exp_f32_e32 v128, v128
	v_exp_f32_e32 v129, v129
	ds_read_b128 v[178:181], v82 offset:4096
	ds_read_b128 v[182:185], v82 offset:4608
	s_waitcnt lgkmcnt(12)
	v_mfma_f32_32x32x16_bf16 v[18:33], v[150:153], v[94:97], v[18:33]
	v_exp_f32_e32 v98, v98
	v_exp_f32_e32 v99, v99
	v_exp_f32_e32 v100, v100
	v_exp_f32_e32 v101, v101
	ds_read_b128 v[186:189], v82 offset:6144
	ds_read_b128 v[130:133], v82 offset:6656
	s_waitcnt lgkmcnt(12)
	v_mfma_f32_32x32x16_bf16 v[34:49], v[150:153], v[66:69], v[34:49]
	v_exp_f32_e32 v102, v102
	v_exp_f32_e32 v103, v103
	v_exp_f32_e32 v104, v104
	v_exp_f32_e32 v105, v105
	s_waitcnt lgkmcnt(10)
	v_mfma_f32_32x32x16_bf16 v[18:33], v[146:149], v[70:73], v[18:33]
	v_exp_f32_e32 v106, v106
	v_exp_f32_e32 v107, v107
	v_exp_f32_e32 v108, v108
	v_exp_f32_e32 v109, v109
	s_waitcnt lgkmcnt(8)
	v_mfma_f32_32x32x16_bf16 v[34:49], v[146:149], v[74:77], v[34:49]
	s_waitcnt vmcnt(2) lgkmcnt(0)
	s_barrier
; #define WAIT_BAR(N) asm volatile("s_waitcnt vmcnt(" #N ") lgkmcnt(0)\n\ts_barrier":::"memory")
;   #define RESC() do{}while(0)
;   #define ROT() do{sl_prev=sl_cur;sl_cur=sl_next;sl_next=(sl_next==(NSLOT-1)*SLOTB)?0:sl_next+SLOTB;}while(0)
; template<int THRL> __device__ __forceinline__ void attn_unit(int b,int h,int qb,const bf16*Q,const bf16*__restrict__ K,const bf16*__restrict__ V,bf16*O,char*shm,float m2){
;     ...
;   int t=1;
;   for(;t+5<NT;t+=2){
;     STEP(pB0,pB1,pA0,pA1,t,true,true,true);     WAIT_BAR(2); RESC(); ROT();
;     STEP(pA0,pA1,pB0,pB1,t+1,true,true,true);   WAIT_BAR(2); RESC(); ROT();
;   }
	s_add_i32 s0, s15, 0x2000
	s_cmpk_lg_i32 s15, 0x4000
	s_cselect_b32 s0, s0, 0
	v_add_u32_e32 v199, s16, v220
	ds_read_b64_tr_b16 v[230:231], v199 offset:24576
	ds_read_b64_tr_b16 v[232:233], v199 offset:25088
	s_waitcnt lgkmcnt(9)
	v_mfma_f32_32x32x16_bf16 v[82:97], v[78:81], v[174:177], v[50:65]
	v_exp_f32_e32 v110, v110
	v_add_f32_e32 v66, v114, v115
	v_add_f32_e32 v66, v116, v66
	v_add_f32_e32 v66, v117, v66
	v_add_f32_e32 v66, v118, v66
	v_add_f32_e32 v66, v119, v66
	v_cvt_pk_bf16_f32 v166, v114, v115
	v_cvt_pk_bf16_f32 v167, v116, v117
	ds_read_b64_tr_b16 v[114:115], v199 offset:28672
	ds_read_b64_tr_b16 v[116:117], v199 offset:29184
	v_add_f32_e32 v66, v120, v66
	v_add_f32_e32 v66, v121, v66
	v_add_f32_e32 v66, v122, v66
	v_add_f32_e32 v146, v123, v66
	s_waitcnt lgkmcnt(10)
	v_mfma_f32_32x32x16_bf16 v[66:81], v[134:137], v[174:177], v[50:65]
	v_exp_f32_e32 v111, v111
	v_cvt_pk_bf16_f32 v168, v118, v119
	v_cvt_pk_bf16_f32 v169, v120, v121
	ds_read_b64_tr_b16 v[118:119], v199 offset:25600
	ds_read_b64_tr_b16 v[120:121], v199 offset:26112
	s_waitcnt lgkmcnt(11)
	v_mfma_f32_32x32x16_bf16 v[82:97], v[138:141], v[170:173], v[82:97]
	v_exp_f32_e32 v112, v112
	v_add_f32_e32 v134, v124, v146
	v_add_f32_e32 v134, v125, v134
	v_add_f32_e32 v134, v126, v134
	v_add_f32_e32 v134, v127, v134
	v_cvt_pk_bf16_f32 v158, v122, v123
	v_cvt_pk_bf16_f32 v159, v124, v125
	ds_read_b64_tr_b16 v[122:123], v199 offset:29696
	ds_read_b64_tr_b16 v[124:125], v199 offset:30208
	s_waitcnt lgkmcnt(12)
	v_mfma_f32_32x32x16_bf16 v[66:81], v[142:145], v[170:173], v[66:81]
	v_exp_f32_e32 v113, v113
	v_add_f32_e32 v134, v128, v134
	v_add_f32_e32 v134, v129, v134
	v_add_f32_e32 v134, v98, v134
	v_add_f32_e32 v134, v99, v134
	v_cvt_pk_bf16_f32 v160, v126, v127
	v_cvt_pk_bf16_f32 v161, v128, v129
	ds_read_b64_tr_b16 v[126:127], v199 offset:26624
	ds_read_b64_tr_b16 v[128:129], v199 offset:27136
	s_waitcnt lgkmcnt(13)
	v_mfma_f32_32x32x16_bf16 v[82:97], v[178:181], v[162:165], v[82:97]
	v_add_f32_e32 v134, v100, v134
	v_add_f32_e32 v134, v101, v134
	v_add_f32_e32 v134, v102, v134
	v_add_f32_e32 v134, v103, v134
	v_cvt_pk_bf16_f32 v150, v98, v99
	v_cvt_pk_bf16_f32 v151, v100, v101
	ds_read_b64_tr_b16 v[234:235], v199 offset:30720
	ds_read_b64_tr_b16 v[236:237], v199 offset:31232
	s_waitcnt lgkmcnt(14)
	v_mfma_f32_32x32x16_bf16 v[66:81], v[182:185], v[162:165], v[66:81]
	v_add_f32_e32 v98, v104, v134
	v_add_f32_e32 v98, v105, v98
	v_add_f32_e32 v98, v106, v98
	v_add_f32_e32 v98, v107, v98
	v_cvt_pk_bf16_f32 v152, v102, v103
	v_cvt_pk_bf16_f32 v153, v104, v105
	ds_read_b64_tr_b16 v[102:103], v199 offset:27648
	ds_read_b64_tr_b16 v[104:105], v199 offset:28160
	s_waitcnt lgkmcnt(14)
	v_mfma_f32_32x32x16_bf16 v[82:97], v[186:189], v[154:157], v[82:97]
	v_add_f32_e32 v98, v108, v98
	v_add_f32_e32 v98, v109, v98
	v_add_f32_e32 v98, v110, v98
	v_add_f32_e32 v98, v111, v98
	v_cvt_pk_bf16_f32 v146, v106, v107
	v_cvt_pk_bf16_f32 v147, v108, v109
	ds_read_b64_tr_b16 v[106:107], v199 offset:31744
	ds_read_b64_tr_b16 v[108:109], v199 offset:32256
	v_mfma_f32_32x32x16_bf16 v[66:81], v[130:133], v[154:157], v[66:81]
	v_add_f32_e32 v98, v112, v98
	v_add_f32_e32 v98, v113, v98
	v_add_f32_e32 v98, 0, v98
	v_cvt_pk_bf16_f32 v148, v110, v111
	v_cvt_pk_bf16_f32 v149, v112, v113
	s_mov_b64 s[16:17], 0x10000
	v_add_f32_e32 v199, v190, v98
	v_lshl_add_u64 v[98:99], v[214:215], 0, s[16:17]
	s_add_i32 s16, s15, s12
	s_mov_b32 s17, m0
	s_mov_b32 m0, s16
	s_nop 0
	global_load_lds_dwordx4 v[98:99], off
	s_mov_b32 m0, s17
	v_lshl_add_u64 v[216:217], v[216:217], 0, s[46:47]
	s_add_i32 s16, s0, s4
	s_mov_b32 s17, m0
	s_mov_b32 m0, s16
	s_nop 0
	global_load_lds_dwordx4 v[216:217], off
	s_mov_b32 m0, s17
	s_waitcnt lgkmcnt(14)
	v_mfma_f32_32x32x16_bf16 v[18:33], v[166:169], v[230:233], v[18:33]
	v_exp_f32_e32 v82, v82
	v_exp_f32_e32 v83, v83
	v_exp_f32_e32 v84, v84
	v_exp_f32_e32 v85, v85
	s_waitcnt lgkmcnt(12)
	v_mfma_f32_32x32x16_bf16 v[34:49], v[166:169], v[114:117], v[34:49]
	v_exp_f32_e32 v86, v86
	v_exp_f32_e32 v87, v87
	v_exp_f32_e32 v88, v88
	v_exp_f32_e32 v89, v89
	v_add_u32_e32 v110, s0, v219
	ds_read_b128 v[98:101], v110
	ds_read_b128 v[182:185], v110 offset:512
	s_waitcnt lgkmcnt(12)
	v_mfma_f32_32x32x16_bf16 v[18:33], v[158:161], v[118:121], v[18:33]
	v_exp_f32_e32 v90, v90
	v_exp_f32_e32 v91, v91
	v_exp_f32_e32 v92, v92
	v_exp_f32_e32 v93, v93
	ds_read_b128 v[186:189], v110 offset:2048
	ds_read_b128 v[178:181], v110 offset:2560
	s_waitcnt lgkmcnt(12)
	v_mfma_f32_32x32x16_bf16 v[34:49], v[158:161], v[122:125], v[34:49]
	v_exp_f32_e32 v94, v94
	v_exp_f32_e32 v95, v95
	v_exp_f32_e32 v96, v96
	v_exp_f32_e32 v97, v97
	ds_read_b128 v[142:145], v110 offset:4096
	ds_read_b128 v[138:141], v110 offset:4608
	s_waitcnt lgkmcnt(12)
	v_mfma_f32_32x32x16_bf16 v[18:33], v[150:153], v[126:129], v[18:33]
	v_exp_f32_e32 v66, v66
	v_exp_f32_e32 v67, v67
	v_exp_f32_e32 v68, v68
	v_exp_f32_e32 v69, v69
	ds_read_b128 v[134:137], v110 offset:6144
	ds_read_b128 v[130:133], v110 offset:6656
	s_waitcnt lgkmcnt(12)
	v_mfma_f32_32x32x16_bf16 v[34:49], v[150:153], v[234:237], v[34:49]
	v_exp_f32_e32 v70, v70
	v_exp_f32_e32 v71, v71
	v_exp_f32_e32 v72, v72
	v_exp_f32_e32 v73, v73
	s_waitcnt lgkmcnt(10)
	v_mfma_f32_32x32x16_bf16 v[18:33], v[146:149], v[102:105], v[18:33]
	v_exp_f32_e32 v74, v74
	v_exp_f32_e32 v75, v75
	v_exp_f32_e32 v76, v76
	v_exp_f32_e32 v77, v77
	s_waitcnt lgkmcnt(8)
	v_mfma_f32_32x32x16_bf16 v[34:49], v[146:149], v[106:109], v[34:49]
	s_add_i32 s18, s0, 0x2000
	s_waitcnt vmcnt(2) lgkmcnt(0)
	s_barrier
; #define WAIT_BAR(N) asm volatile("s_waitcnt vmcnt(" #N ") lgkmcnt(0)\n\ts_barrier":::"memory")
;   #define RESC() do{}while(0)
;   #define ROT() do{sl_prev=sl_cur;sl_cur=sl_next;sl_next=(sl_next==(NSLOT-1)*SLOTB)?0:sl_next+SLOTB;}while(0)
;   #define ENDW(tt) do{ if((tt)+3<NT){WAIT_BAR(2);} else if((tt)+2<NT){WAIT_BAR(1);} else {WAIT_BAR(0);} }while(0)
; template<int THRL> __device__ __forceinline__ void attn_unit(int b,int h,int qb,const bf16*Q,const bf16*__restrict__ K,const bf16*__restrict__ V,bf16*O,char*shm,float m2){
;     ...
;   int t=1;
;   for(;t+5<NT;t+=2){
;     STEP(pB0,pB1,pA0,pA1,t,true,true,true);     WAIT_BAR(2); RESC(); ROT();
;     STEP(pA0,pA1,pB0,pB1,t+1,true,true,true);   WAIT_BAR(2); RESC(); ROT();
;   }
;     ...
;   for(;t+1<NT;t+=2){
;     STEP(pB0,pB1,pA0,pA1,t,(t+3<NT),(t+1<NT),(t+1<NT));       ENDW(t);   RESC(); ROT();
;     STEP(pA0,pA1,pB0,pB1,t+1,(t+4<NT),(t+2<NT),(t+2<NT));     ENDW(t+1); RESC(); ROT();
	s_cmpk_lg_i32 s0, 0x4000
	s_mov_b32 s17, s15
	s_cselect_b32 s15, s18, 0
	s_add_i32 s14, s14, 2
	v_lshl_add_u64 v[214:215], v[214:215], 0, s[46:47]
	s_mov_b32 s16, s0
	s_cmpk_gt_u32 s14, 0x78
	s_cbranch_scc0 .LBB0_829
	v_exp_f32_e32 v78, v78
	v_exp_f32_e32 v79, v79
	v_exp_f32_e32 v80, v80
	v_exp_f32_e32 v81, v81
	s_and_b32 s0, s13, 0x3fffffc0
	s_lshl_b32 s0, s0, 2
	s_add_i32 s0, s0, 0
	ds_read_b64_tr_b16 v[214:215], v220 offset:40960
	ds_read_b64_tr_b16 v[216:217], v220 offset:41472
	v_add_f32_e32 v102, v82, v83
	v_add_f32_e32 v102, v84, v102
	v_add_f32_e32 v102, v85, v102
	v_add_f32_e32 v102, v86, v102
	v_add_f32_e32 v102, v87, v102
	v_cvt_pk_bf16_f32 v166, v82, v83
	v_cvt_pk_bf16_f32 v167, v84, v85
	s_waitcnt lgkmcnt(9)
	v_mfma_f32_32x32x16_bf16 v[114:129], v[98:101], v[174:177], v[50:65]
	ds_read_b64_tr_b16 v[82:83], v220 offset:45056
	ds_read_b64_tr_b16 v[84:85], v220 offset:45568
	v_add_f32_e32 v98, v88, v102
	v_add_f32_e32 v98, v89, v98
	v_add_f32_e32 v98, v90, v98
	v_add_f32_e32 v146, v91, v98
	v_cvt_pk_bf16_f32 v168, v86, v87
	v_cvt_pk_bf16_f32 v169, v88, v89
	s_waitcnt lgkmcnt(10)
	v_mfma_f32_32x32x16_bf16 v[98:113], v[182:185], v[174:177], v[50:65]
	ds_read_b64_tr_b16 v[86:87], v220 offset:41984
	ds_read_b64_tr_b16 v[88:89], v220 offset:42496
	v_add_f32_e32 v146, v92, v146
	v_add_f32_e32 v146, v93, v146
	v_add_f32_e32 v146, v94, v146
	v_add_f32_e32 v146, v95, v146
	v_cvt_pk_bf16_f32 v158, v90, v91
	v_cvt_pk_bf16_f32 v159, v92, v93
	s_waitcnt lgkmcnt(11)
	v_mfma_f32_32x32x16_bf16 v[114:129], v[186:189], v[170:173], v[114:129]
	ds_read_b64_tr_b16 v[90:91], v220 offset:46080
	ds_read_b64_tr_b16 v[92:93], v220 offset:46592
	v_add_f32_e32 v146, v96, v146
	v_add_f32_e32 v146, v97, v146
	v_add_f32_e32 v146, v66, v146
	v_add_f32_e32 v146, v67, v146
	v_cvt_pk_bf16_f32 v160, v94, v95
	v_cvt_pk_bf16_f32 v161, v96, v97
	s_waitcnt lgkmcnt(12)
	v_mfma_f32_32x32x16_bf16 v[98:113], v[178:181], v[170:173], v[98:113]
	ds_read_b64_tr_b16 v[94:95], v220 offset:43008
	ds_read_b64_tr_b16 v[96:97], v220 offset:43520
	s_waitcnt lgkmcnt(13)
	v_mfma_f32_32x32x16_bf16 v[114:129], v[142:145], v[162:165], v[114:129]
	v_add_f32_e32 v142, v68, v146
	v_add_f32_e32 v142, v69, v142
	v_add_f32_e32 v142, v70, v142
	v_add_f32_e32 v142, v71, v142
	v_cvt_pk_bf16_f32 v150, v66, v67
	v_cvt_pk_bf16_f32 v151, v68, v69
	ds_read_b64_tr_b16 v[66:67], v220 offset:47104
	ds_read_b64_tr_b16 v[68:69], v220 offset:47616
	s_waitcnt lgkmcnt(14)
	v_mfma_f32_32x32x16_bf16 v[98:113], v[138:141], v[162:165], v[98:113]
	v_add_f32_e32 v138, v72, v142
	v_add_f32_e32 v138, v73, v138
	v_add_f32_e32 v138, v74, v138
	v_add_f32_e32 v138, v75, v138
	v_cvt_pk_bf16_f32 v152, v70, v71
	v_cvt_pk_bf16_f32 v153, v72, v73
	ds_read_b64_tr_b16 v[70:71], v220 offset:44032
	ds_read_b64_tr_b16 v[72:73], v220 offset:44544
	s_waitcnt lgkmcnt(14)
	v_mfma_f32_32x32x16_bf16 v[114:129], v[134:137], v[154:157], v[114:129]
	v_add_f32_e32 v134, v76, v138
	v_add_f32_e32 v134, v77, v134
	v_add_f32_e32 v134, v78, v134
	v_add_f32_e32 v134, v79, v134
	v_cvt_pk_bf16_f32 v146, v74, v75
	v_cvt_pk_bf16_f32 v147, v76, v77
	ds_read_b64_tr_b16 v[74:75], v220 offset:48128
	ds_read_b64_tr_b16 v[76:77], v220 offset:48640
	v_mfma_f32_32x32x16_bf16 v[98:113], v[130:133], v[154:157], v[98:113]
	v_add_f32_e32 v130, v80, v134
	v_add_f32_e32 v130, v81, v130
	v_add_f32_e32 v130, 0, v130
	v_cvt_pk_bf16_f32 v148, v78, v79
	v_cvt_pk_bf16_f32 v149, v80, v81
	v_lshl_add_u64 v[78:79], v[212:213], 0, s[50:51]
	s_mov_b32 s13, m0
	s_mov_b32 m0, s12
	s_nop 0
	global_load_lds_dwordx4 v[78:79], off
	s_mov_b32 m0, s13
	s_mov_b64 s[12:13], 0x1f0000
	s_cmp_lg_u32 0, -1
	v_lshl_add_u64 v[78:79], v[210:211], 0, s[12:13]
	s_cselect_b32 s12, 0, 0
	s_add_i32 s12, s12, s5
	s_add_i32 s5, s12, 0x8000
	s_mov_b32 s13, m0
	s_mov_b32 m0, s5
	s_nop 0
	global_load_lds_dwordx4 v[78:79], off
	s_mov_b32 m0, s13
	v_add_f32_e32 v190, v199, v130
	s_waitcnt lgkmcnt(14)
	v_mfma_f32_32x32x16_bf16 v[18:33], v[166:169], v[214:217], v[18:33]
	v_exp_f32_e32 v114, v114
	v_exp_f32_e32 v115, v115
	v_exp_f32_e32 v116, v116
	v_exp_f32_e32 v117, v117
	s_waitcnt lgkmcnt(12)
	v_mfma_f32_32x32x16_bf16 v[34:49], v[166:169], v[82:85], v[34:49]
	v_exp_f32_e32 v118, v118
	v_exp_f32_e32 v119, v119
	v_exp_f32_e32 v120, v120
	v_exp_f32_e32 v121, v121
	ds_read_b128 v[78:81], v219 offset:8192
	ds_read_b128 v[178:181], v219 offset:8704
	s_waitcnt lgkmcnt(12)
	v_mfma_f32_32x32x16_bf16 v[18:33], v[158:161], v[86:89], v[18:33]
	v_exp_f32_e32 v122, v122
	v_exp_f32_e32 v123, v123
	v_exp_f32_e32 v124, v124
	v_exp_f32_e32 v125, v125
	ds_read_b128 v[86:89], v219 offset:10240
	ds_read_b128 v[182:185], v219 offset:10752
	s_waitcnt lgkmcnt(12)
	v_mfma_f32_32x32x16_bf16 v[34:49], v[158:161], v[90:93], v[34:49]
	v_exp_f32_e32 v126, v126
	v_exp_f32_e32 v127, v127
	v_exp_f32_e32 v128, v128
	v_exp_f32_e32 v129, v129
	ds_read_b128 v[90:93], v219 offset:12288
	ds_read_b128 v[186:189], v219 offset:12800
	s_waitcnt lgkmcnt(12)
	v_mfma_f32_32x32x16_bf16 v[18:33], v[150:153], v[94:97], v[18:33]
	v_exp_f32_e32 v98, v98
	v_exp_f32_e32 v99, v99
	v_exp_f32_e32 v100, v100
	v_exp_f32_e32 v101, v101
	ds_read_b128 v[94:97], v219 offset:14336
	ds_read_b128 v[82:85], v219 offset:14848
	s_waitcnt lgkmcnt(12)
	v_mfma_f32_32x32x16_bf16 v[34:49], v[150:153], v[66:69], v[34:49]
	v_exp_f32_e32 v102, v102
	v_exp_f32_e32 v103, v103
	v_exp_f32_e32 v104, v104
	v_exp_f32_e32 v105, v105
	s_waitcnt lgkmcnt(10)
	v_mfma_f32_32x32x16_bf16 v[18:33], v[146:149], v[70:73], v[18:33]
	v_exp_f32_e32 v106, v106
	v_exp_f32_e32 v107, v107
	v_exp_f32_e32 v108, v108
	v_exp_f32_e32 v109, v109
	s_waitcnt lgkmcnt(8)
	v_mfma_f32_32x32x16_bf16 v[34:49], v[146:149], v[74:77], v[34:49]
	v_exp_f32_e32 v110, v110
	v_exp_f32_e32 v111, v111
	v_exp_f32_e32 v112, v112
	v_exp_f32_e32 v113, v113
	s_waitcnt vmcnt(2) lgkmcnt(0)
	s_barrier
; #define WAIT_BAR(N) asm volatile("s_waitcnt vmcnt(" #N ") lgkmcnt(0)\n\ts_barrier":::"memory")
;   #define RESC() do{}while(0)
;   #define ROT() do{sl_prev=sl_cur;sl_cur=sl_next;sl_next=(sl_next==(NSLOT-1)*SLOTB)?0:sl_next+SLOTB;}while(0)
;   #define ENDW(tt) do{ if((tt)+3<NT){WAIT_BAR(2);} else if((tt)+2<NT){WAIT_BAR(1);} else {WAIT_BAR(0);} }while(0)
; template<int THRL> __device__ __forceinline__ void attn_unit(int b,int h,int qb,const bf16*Q,const bf16*__restrict__ K,const bf16*__restrict__ V,bf16*O,char*shm,float m2){
;     ...
;   int t=1;
;   for(;t+5<NT;t+=2){
;     STEP(pB0,pB1,pA0,pA1,t,true,true,true);     WAIT_BAR(2); RESC(); ROT();
;     STEP(pA0,pA1,pB0,pB1,t+1,true,true,true);   WAIT_BAR(2); RESC(); ROT();
;   }
;     ...
;   for(;t+1<NT;t+=2){
;     STEP(pB0,pB1,pA0,pA1,t,(t+3<NT),(t+1<NT),(t+1<NT));       ENDW(t);   RESC(); ROT();
;     STEP(pA0,pA1,pB0,pB1,t+1,(t+4<NT),(t+2<NT),(t+2<NT));     ENDW(t+1); RESC(); ROT();
	ds_read_b64_tr_b16 v[214:215], v220 offset:24576
	ds_read_b64_tr_b16 v[216:217], v220 offset:25088
	v_add_f32_e32 v66, v114, v115
	v_add_f32_e32 v66, v116, v66
	v_add_f32_e32 v66, v117, v66
	v_add_f32_e32 v66, v118, v66
	v_add_f32_e32 v66, v119, v66
	v_cvt_pk_bf16_f32 v166, v114, v115
	v_cvt_pk_bf16_f32 v167, v116, v117
	s_waitcnt lgkmcnt(9)
	v_mfma_f32_32x32x16_bf16 v[130:145], v[78:81], v[174:177], v[50:65]
	ds_read_b64_tr_b16 v[114:115], v220 offset:28672
	ds_read_b64_tr_b16 v[116:117], v220 offset:29184
	v_add_f32_e32 v66, v120, v66
	v_add_f32_e32 v66, v121, v66
	v_add_f32_e32 v66, v122, v66
	v_add_f32_e32 v146, v123, v66
	s_waitcnt lgkmcnt(10)
	v_mfma_f32_32x32x16_bf16 v[66:81], v[178:181], v[174:177], v[50:65]
	v_cvt_pk_bf16_f32 v168, v118, v119
	v_cvt_pk_bf16_f32 v169, v120, v121
	ds_read_b64_tr_b16 v[118:119], v220 offset:25600
	ds_read_b64_tr_b16 v[120:121], v220 offset:26112
	s_waitcnt lgkmcnt(11)
	v_mfma_f32_32x32x16_bf16 v[130:145], v[86:89], v[170:173], v[130:145]
	v_add_f32_e32 v86, v124, v146
	v_add_f32_e32 v86, v125, v86
	v_add_f32_e32 v86, v126, v86
	v_add_f32_e32 v146, v127, v86
	v_cvt_pk_bf16_f32 v158, v122, v123
	v_cvt_pk_bf16_f32 v159, v124, v125
	ds_read_b64_tr_b16 v[86:87], v220 offset:29696
	ds_read_b64_tr_b16 v[88:89], v220 offset:30208
	s_waitcnt lgkmcnt(12)
	v_mfma_f32_32x32x16_bf16 v[66:81], v[182:185], v[170:173], v[66:81]
	v_add_f32_e32 v122, v128, v146
	v_add_f32_e32 v122, v129, v122
	v_add_f32_e32 v122, v98, v122
	v_add_f32_e32 v146, v99, v122
	v_cvt_pk_bf16_f32 v160, v126, v127
	v_cvt_pk_bf16_f32 v161, v128, v129
	ds_read_b64_tr_b16 v[122:123], v220 offset:26624
	ds_read_b64_tr_b16 v[124:125], v220 offset:27136
	s_waitcnt lgkmcnt(13)
	v_mfma_f32_32x32x16_bf16 v[130:145], v[90:93], v[162:165], v[130:145]
	v_add_f32_e32 v90, v100, v146
	v_add_f32_e32 v90, v101, v90
	v_add_f32_e32 v90, v102, v90
	v_add_f32_e32 v126, v103, v90
	v_cvt_pk_bf16_f32 v150, v98, v99
	v_cvt_pk_bf16_f32 v151, v100, v101
	ds_read_b64_tr_b16 v[90:91], v220 offset:30720
	ds_read_b64_tr_b16 v[92:93], v220 offset:31232
	s_waitcnt lgkmcnt(14)
	v_mfma_f32_32x32x16_bf16 v[66:81], v[186:189], v[162:165], v[66:81]
	v_add_f32_e32 v98, v104, v126
	v_add_f32_e32 v98, v105, v98
	v_add_f32_e32 v98, v106, v98
	v_add_f32_e32 v98, v107, v98
	v_cvt_pk_bf16_f32 v152, v102, v103
	v_cvt_pk_bf16_f32 v153, v104, v105
	ds_read_b64_tr_b16 v[102:103], v220 offset:27648
	ds_read_b64_tr_b16 v[104:105], v220 offset:28160
	s_waitcnt lgkmcnt(14)
	v_mfma_f32_32x32x16_bf16 v[130:145], v[94:97], v[154:157], v[130:145]
	v_add_f32_e32 v94, v108, v98
	v_add_f32_e32 v94, v109, v94
	v_add_f32_e32 v94, v110, v94
	v_add_f32_e32 v98, v111, v94
	v_cvt_pk_bf16_f32 v146, v106, v107
	v_cvt_pk_bf16_f32 v147, v108, v109
	ds_read_b64_tr_b16 v[94:95], v220 offset:31744
	ds_read_b64_tr_b16 v[96:97], v220 offset:32256
	v_mfma_f32_32x32x16_bf16 v[66:81], v[82:85], v[154:157], v[66:81]
	v_add_f32_e32 v82, v112, v98
	v_add_f32_e32 v82, v113, v82
	v_add_f32_e32 v82, 0, v82
	v_cvt_pk_bf16_f32 v148, v110, v111
	v_cvt_pk_bf16_f32 v149, v112, v113
	s_nop 0
	v_add_f32_e32 v190, v190, v82
	v_lshl_add_u64 v[82:83], v[212:213], 0, s[52:53]
	s_add_i32 s13, s12, 0x2000
	s_mov_b32 s14, m0
	s_mov_b32 m0, s13
	s_nop 0
	global_load_lds_dwordx4 v[82:83], off
	s_mov_b32 m0, s14
	s_mov_b64 s[14:15], 0x1f4000
	v_lshl_add_u64 v[82:83], v[210:211], 0, s[14:15]
	s_add_i32 s12, s12, 0xa000
	s_mov_b32 s13, m0
	s_mov_b32 m0, s12
	s_nop 0
	global_load_lds_dwordx4 v[82:83], off
	s_mov_b32 m0, s13
	s_waitcnt lgkmcnt(14)
	v_mfma_f32_32x32x16_bf16 v[18:33], v[166:169], v[214:217], v[18:33]
	v_exp_f32_e32 v130, v130
	v_exp_f32_e32 v131, v131
	v_exp_f32_e32 v132, v132
	v_exp_f32_e32 v133, v133
	s_waitcnt lgkmcnt(12)
	v_mfma_f32_32x32x16_bf16 v[34:49], v[166:169], v[114:117], v[34:49]
	v_exp_f32_e32 v134, v134
	v_exp_f32_e32 v135, v135
	v_exp_f32_e32 v136, v136
	v_exp_f32_e32 v137, v137
	ds_read_b128 v[82:85], v219 offset:16384
	ds_read_b128 v[106:109], v219 offset:16896
	s_waitcnt lgkmcnt(12)
	v_mfma_f32_32x32x16_bf16 v[18:33], v[158:161], v[118:121], v[18:33]
	v_exp_f32_e32 v138, v138
	v_exp_f32_e32 v139, v139
	v_exp_f32_e32 v140, v140
	v_exp_f32_e32 v141, v141
	ds_read_b128 v[110:113], v219 offset:18432
	ds_read_b128 v[178:181], v219 offset:18944
	s_waitcnt lgkmcnt(12)
	v_mfma_f32_32x32x16_bf16 v[34:49], v[158:161], v[86:89], v[34:49]
	v_exp_f32_e32 v142, v142
	v_exp_f32_e32 v143, v143
	v_exp_f32_e32 v144, v144
	v_exp_f32_e32 v145, v145
	ds_read_b128 v[182:185], v219 offset:20480
	ds_read_b128 v[186:189], v219 offset:20992
	s_waitcnt lgkmcnt(12)
	v_mfma_f32_32x32x16_bf16 v[18:33], v[150:153], v[122:125], v[18:33]
	v_exp_f32_e32 v66, v66
	v_exp_f32_e32 v67, v67
	v_exp_f32_e32 v68, v68
	v_exp_f32_e32 v69, v69
	ds_read_b128 v[212:215], v219 offset:22528
	ds_read_b128 v[98:101], v219 offset:23040
	s_waitcnt lgkmcnt(12)
	v_mfma_f32_32x32x16_bf16 v[34:49], v[150:153], v[90:93], v[34:49]
	v_exp_f32_e32 v70, v70
	v_exp_f32_e32 v71, v71
	v_exp_f32_e32 v72, v72
	v_exp_f32_e32 v73, v73
	s_waitcnt lgkmcnt(10)
	v_mfma_f32_32x32x16_bf16 v[18:33], v[146:149], v[102:105], v[18:33]
	v_exp_f32_e32 v74, v74
	v_exp_f32_e32 v75, v75
	v_exp_f32_e32 v76, v76
	v_exp_f32_e32 v77, v77
	s_waitcnt lgkmcnt(8)
	v_mfma_f32_32x32x16_bf16 v[34:49], v[146:149], v[94:97], v[34:49]
	v_exp_f32_e32 v78, v78
	v_exp_f32_e32 v79, v79
	v_exp_f32_e32 v80, v80
	v_exp_f32_e32 v81, v81
	s_waitcnt vmcnt(2) lgkmcnt(0)
	s_barrier
; #define WAIT_BAR(N) asm volatile("s_waitcnt vmcnt(" #N ") lgkmcnt(0)\n\ts_barrier":::"memory")
;   #define RESC() do{}while(0)
;   #define ROT() do{sl_prev=sl_cur;sl_cur=sl_next;sl_next=(sl_next==(NSLOT-1)*SLOTB)?0:sl_next+SLOTB;}while(0)
;   #define ENDW(tt) do{ if((tt)+3<NT){WAIT_BAR(2);} else if((tt)+2<NT){WAIT_BAR(1);} else {WAIT_BAR(0);} }while(0)
; template<int THRL> __device__ __forceinline__ void attn_unit(int b,int h,int qb,const bf16*Q,const bf16*__restrict__ K,const bf16*__restrict__ V,bf16*O,char*shm,float m2){
;     ...
;   int t=1;
;   for(;t+5<NT;t+=2){
;     STEP(pB0,pB1,pA0,pA1,t,true,true,true);     WAIT_BAR(2); RESC(); ROT();
;     STEP(pA0,pA1,pB0,pB1,t+1,true,true,true);   WAIT_BAR(2); RESC(); ROT();
;   }
;     ...
;   for(;t+1<NT;t+=2){
;     STEP(pB0,pB1,pA0,pA1,t,(t+3<NT),(t+1<NT),(t+1<NT));       ENDW(t);   RESC(); ROT();
;     STEP(pA0,pA1,pB0,pB1,t+1,(t+4<NT),(t+2<NT),(t+2<NT));     ENDW(t+1); RESC(); ROT();
	ds_read_b64_tr_b16 v[102:103], v220 offset:32768
	ds_read_b64_tr_b16 v[104:105], v220 offset:33280
	v_add_f32_e32 v86, v130, v131
	v_add_f32_e32 v86, v132, v86
	v_add_f32_e32 v86, v133, v86
	v_add_f32_e32 v86, v134, v86
	v_add_f32_e32 v86, v135, v86
	v_cvt_pk_bf16_f32 v166, v130, v131
	v_cvt_pk_bf16_f32 v167, v132, v133
	s_waitcnt lgkmcnt(9)
	v_mfma_f32_32x32x16_bf16 v[114:129], v[82:85], v[174:177], v[50:65]
	ds_read_b64_tr_b16 v[130:131], v220 offset:36864
	ds_read_b64_tr_b16 v[132:133], v220 offset:37376
	v_add_f32_e32 v82, v136, v86
	v_add_f32_e32 v82, v137, v82
	v_add_f32_e32 v82, v138, v82
	v_add_f32_e32 v146, v139, v82
	v_cvt_pk_bf16_f32 v168, v134, v135
	v_cvt_pk_bf16_f32 v169, v136, v137
	s_waitcnt lgkmcnt(10)
	v_mfma_f32_32x32x16_bf16 v[82:97], v[106:109], v[174:177], v[50:65]
	ds_read_b64_tr_b16 v[106:107], v220 offset:33792
	ds_read_b64_tr_b16 v[108:109], v220 offset:34304
	s_waitcnt lgkmcnt(11)
	v_mfma_f32_32x32x16_bf16 v[114:129], v[110:113], v[170:173], v[114:129]
	v_add_f32_e32 v110, v140, v146
	v_add_f32_e32 v110, v141, v110
	v_add_f32_e32 v110, v142, v110
	v_add_f32_e32 v134, v143, v110
	v_cvt_pk_bf16_f32 v158, v138, v139
	v_cvt_pk_bf16_f32 v159, v140, v141
	ds_read_b64_tr_b16 v[110:111], v220 offset:37888
	ds_read_b64_tr_b16 v[112:113], v220 offset:38400
	v_add_f32_e32 v134, v144, v134
	v_add_f32_e32 v134, v145, v134
	v_add_f32_e32 v134, v66, v134
	v_add_f32_e32 v138, v67, v134
	v_cvt_pk_bf16_f32 v160, v142, v143
	v_cvt_pk_bf16_f32 v161, v144, v145
	s_waitcnt lgkmcnt(12)
	v_mfma_f32_32x32x16_bf16 v[82:97], v[178:181], v[170:173], v[82:97]
	ds_read_b64_tr_b16 v[134:135], v220 offset:34816
	ds_read_b64_tr_b16 v[136:137], v220 offset:35328
	v_add_f32_e32 v138, v68, v138
	v_add_f32_e32 v138, v69, v138
	v_add_f32_e32 v138, v70, v138
	v_add_f32_e32 v138, v71, v138
	v_cvt_pk_bf16_f32 v150, v66, v67
	v_cvt_pk_bf16_f32 v151, v68, v69
	s_waitcnt lgkmcnt(13)
	v_mfma_f32_32x32x16_bf16 v[114:129], v[182:185], v[162:165], v[114:129]
	ds_read_b64_tr_b16 v[66:67], v220 offset:38912
	ds_read_b64_tr_b16 v[68:69], v220 offset:39424
	v_add_f32_e32 v138, v72, v138
	v_add_f32_e32 v138, v73, v138
	v_add_f32_e32 v138, v74, v138
	v_add_f32_e32 v138, v75, v138
	v_cvt_pk_bf16_f32 v152, v70, v71
	v_cvt_pk_bf16_f32 v153, v72, v73
	s_waitcnt lgkmcnt(14)
	v_mfma_f32_32x32x16_bf16 v[82:97], v[186:189], v[162:165], v[82:97]
	ds_read_b64_tr_b16 v[70:71], v220 offset:35840
	ds_read_b64_tr_b16 v[72:73], v220 offset:36352
	v_add_f32_e32 v138, v76, v138
	v_add_f32_e32 v138, v77, v138
	v_add_f32_e32 v138, v78, v138
	v_add_f32_e32 v138, v79, v138
	v_cvt_pk_bf16_f32 v146, v74, v75
	v_cvt_pk_bf16_f32 v147, v76, v77
	s_waitcnt lgkmcnt(14)
	v_mfma_f32_32x32x16_bf16 v[114:129], v[212:215], v[154:157], v[114:129]
	ds_read_b64_tr_b16 v[74:75], v220 offset:39936
	ds_read_b64_tr_b16 v[76:77], v220 offset:40448
	v_mfma_f32_32x32x16_bf16 v[82:97], v[98:101], v[154:157], v[82:97]
	v_add_f32_e32 v98, v80, v138
	v_add_f32_e32 v98, v81, v98
	v_add_f32_e32 v98, 0, v98
	v_cvt_pk_bf16_f32 v148, v78, v79
	v_cvt_pk_bf16_f32 v149, v80, v81
	v_lshl_add_u64 v[78:79], v[210:211], 0, s[50:51]
	s_mov_b32 s12, m0
	s_mov_b32 m0, s4
	s_nop 0
	global_load_lds_dwordx4 v[78:79], off
	s_mov_b32 m0, s12
	v_add_f32_e32 v190, v190, v98
	s_waitcnt lgkmcnt(14)
	v_mfma_f32_32x32x16_bf16 v[18:33], v[166:169], v[102:105], v[18:33]
	v_exp_f32_e32 v114, v114
	v_exp_f32_e32 v115, v115
	v_exp_f32_e32 v116, v116
	v_exp_f32_e32 v117, v117
	s_waitcnt lgkmcnt(12)
	v_mfma_f32_32x32x16_bf16 v[34:49], v[166:169], v[130:133], v[34:49]
	v_exp_f32_e32 v118, v118
	v_exp_f32_e32 v119, v119
	v_exp_f32_e32 v120, v120
	v_exp_f32_e32 v121, v121
	ds_read_b128 v[78:81], v219
	ds_read_b128 v[138:141], v219 offset:512
	s_waitcnt lgkmcnt(12)
	v_mfma_f32_32x32x16_bf16 v[18:33], v[158:161], v[106:109], v[18:33]
	v_exp_f32_e32 v122, v122
	v_exp_f32_e32 v123, v123
	v_exp_f32_e32 v124, v124
	v_exp_f32_e32 v125, v125
	ds_read_b128 v[142:145], v219 offset:2048
	ds_read_b128 v[178:181], v219 offset:2560
	s_waitcnt lgkmcnt(12)
	v_mfma_f32_32x32x16_bf16 v[34:49], v[158:161], v[110:113], v[34:49]
	v_exp_f32_e32 v126, v126
	v_exp_f32_e32 v127, v127
	v_exp_f32_e32 v128, v128
	v_exp_f32_e32 v129, v129
	ds_read_b128 v[182:185], v219 offset:4096
	ds_read_b128 v[186:189], v219 offset:4608
	s_waitcnt lgkmcnt(12)
	v_mfma_f32_32x32x16_bf16 v[18:33], v[150:153], v[134:137], v[18:33]
	v_exp_f32_e32 v82, v82
	v_exp_f32_e32 v83, v83
	v_exp_f32_e32 v84, v84
	v_exp_f32_e32 v85, v85
	ds_read_b128 v[134:137], v219 offset:6144
	ds_read_b128 v[130:133], v219 offset:6656
	s_waitcnt lgkmcnt(12)
	v_mfma_f32_32x32x16_bf16 v[34:49], v[150:153], v[66:69], v[34:49]
	v_exp_f32_e32 v86, v86
	v_exp_f32_e32 v87, v87
	v_exp_f32_e32 v88, v88
	v_exp_f32_e32 v89, v89
	s_waitcnt lgkmcnt(10)
	v_mfma_f32_32x32x16_bf16 v[18:33], v[146:149], v[70:73], v[18:33]
	v_exp_f32_e32 v90, v90
	v_exp_f32_e32 v91, v91
	v_exp_f32_e32 v92, v92
	v_exp_f32_e32 v93, v93
	s_waitcnt lgkmcnt(8)
	v_mfma_f32_32x32x16_bf16 v[34:49], v[146:149], v[74:77], v[34:49]
	v_exp_f32_e32 v94, v94
	v_exp_f32_e32 v95, v95
	v_exp_f32_e32 v96, v96
	v_exp_f32_e32 v97, v97
	s_waitcnt vmcnt(1) lgkmcnt(0)
	s_barrier
; #define WAIT_BAR(N) asm volatile("s_waitcnt vmcnt(" #N ") lgkmcnt(0)\n\ts_barrier":::"memory")
;   #define RESC() do{}while(0)
;   #define ROT() do{sl_prev=sl_cur;sl_cur=sl_next;sl_next=(sl_next==(NSLOT-1)*SLOTB)?0:sl_next+SLOTB;}while(0)
;   #define ENDW(tt) do{ if((tt)+3<NT){WAIT_BAR(2);} else if((tt)+2<NT){WAIT_BAR(1);} else {WAIT_BAR(0);} }while(0)
; template<int THRL> __device__ __forceinline__ void attn_unit(int b,int h,int qb,const bf16*Q,const bf16*__restrict__ K,const bf16*__restrict__ V,bf16*O,char*shm,float m2){
;     ...
;   int t=1;
;   for(;t+5<NT;t+=2){
;     STEP(pB0,pB1,pA0,pA1,t,true,true,true);     WAIT_BAR(2); RESC(); ROT();
;     STEP(pA0,pA1,pB0,pB1,t+1,true,true,true);   WAIT_BAR(2); RESC(); ROT();
;   }
;     ...
;   for(;t+1<NT;t+=2){
;     STEP(pB0,pB1,pA0,pA1,t,(t+3<NT),(t+1<NT),(t+1<NT));       ENDW(t);   RESC(); ROT();
;     STEP(pA0,pA1,pB0,pB1,t+1,(t+4<NT),(t+2<NT),(t+2<NT));     ENDW(t+1); RESC(); ROT();
	ds_read_b64_tr_b16 v[212:213], v220 offset:40960
	ds_read_b64_tr_b16 v[214:215], v220 offset:41472
	v_add_f32_e32 v66, v114, v115
	v_add_f32_e32 v66, v116, v66
	v_add_f32_e32 v66, v117, v66
	v_add_f32_e32 v66, v118, v66
	v_add_f32_e32 v66, v119, v66
	v_cvt_pk_bf16_f32 v166, v114, v115
	v_cvt_pk_bf16_f32 v167, v116, v117
	s_waitcnt lgkmcnt(9)
	v_mfma_f32_32x32x16_bf16 v[98:113], v[78:81], v[174:177], v[50:65]
	ds_read_b64_tr_b16 v[114:115], v220 offset:45056
	ds_read_b64_tr_b16 v[116:117], v220 offset:45568
	v_add_f32_e32 v66, v120, v66
	v_add_f32_e32 v66, v121, v66
	v_add_f32_e32 v66, v122, v66
	v_add_f32_e32 v146, v123, v66
	s_waitcnt lgkmcnt(10)
	v_mfma_f32_32x32x16_bf16 v[66:81], v[138:141], v[174:177], v[50:65]
	v_cvt_pk_bf16_f32 v168, v118, v119
	v_cvt_pk_bf16_f32 v169, v120, v121
	ds_read_b64_tr_b16 v[138:139], v220 offset:41984
	ds_read_b64_tr_b16 v[140:141], v220 offset:42496
	v_add_f32_e32 v118, v124, v146
	v_add_f32_e32 v118, v125, v118
	v_add_f32_e32 v118, v126, v118
	v_add_f32_e32 v118, v127, v118
	v_cvt_pk_bf16_f32 v158, v122, v123
	v_cvt_pk_bf16_f32 v159, v124, v125
	s_waitcnt lgkmcnt(11)
	v_mfma_f32_32x32x16_bf16 v[98:113], v[142:145], v[170:173], v[98:113]
	ds_read_b64_tr_b16 v[120:121], v220 offset:46080
	ds_read_b64_tr_b16 v[122:123], v220 offset:46592
	s_waitcnt lgkmcnt(12)
	v_mfma_f32_32x32x16_bf16 v[66:81], v[178:181], v[170:173], v[66:81]
	v_add_f32_e32 v118, v128, v118
	v_add_f32_e32 v118, v129, v118
	v_add_f32_e32 v118, v82, v118
	v_add_f32_e32 v118, v83, v118
	v_cvt_pk_bf16_f32 v160, v126, v127
	v_cvt_pk_bf16_f32 v161, v128, v129
	ds_read_b64_tr_b16 v[124:125], v220 offset:43008
	ds_read_b64_tr_b16 v[126:127], v220 offset:43520
	v_add_f32_e32 v118, v84, v118
	v_add_f32_e32 v118, v85, v118
	v_add_f32_e32 v118, v86, v118
	v_add_f32_e32 v118, v87, v118
	v_cvt_pk_bf16_f32 v150, v82, v83
	v_cvt_pk_bf16_f32 v151, v84, v85
	s_waitcnt lgkmcnt(13)
	v_mfma_f32_32x32x16_bf16 v[98:113], v[182:185], v[162:165], v[98:113]
	ds_read_b64_tr_b16 v[82:83], v220 offset:47104
	ds_read_b64_tr_b16 v[84:85], v220 offset:47616
	s_waitcnt lgkmcnt(14)
	v_mfma_f32_32x32x16_bf16 v[66:81], v[186:189], v[162:165], v[66:81]
	v_add_f32_e32 v118, v88, v118
	v_add_f32_e32 v118, v89, v118
	v_add_f32_e32 v118, v90, v118
	v_add_f32_e32 v118, v91, v118
	v_cvt_pk_bf16_f32 v152, v86, v87
	v_cvt_pk_bf16_f32 v153, v88, v89
	ds_read_b64_tr_b16 v[86:87], v220 offset:44032
	ds_read_b64_tr_b16 v[88:89], v220 offset:44544
	v_add_f32_e32 v118, v92, v118
	v_add_f32_e32 v118, v93, v118
	v_add_f32_e32 v118, v94, v118
	v_add_f32_e32 v118, v95, v118
	v_cvt_pk_bf16_f32 v146, v90, v91
	v_cvt_pk_bf16_f32 v147, v92, v93
	s_waitcnt lgkmcnt(14)
	v_mfma_f32_32x32x16_bf16 v[98:113], v[134:137], v[154:157], v[98:113]
	ds_read_b64_tr_b16 v[90:91], v220 offset:48128
	ds_read_b64_tr_b16 v[92:93], v220 offset:48640
	v_mfma_f32_32x32x16_bf16 v[66:81], v[130:133], v[154:157], v[66:81]
	v_add_f32_e32 v118, v96, v118
	v_add_f32_e32 v118, v97, v118
	v_add_f32_e32 v118, 0, v118
	v_cvt_pk_bf16_f32 v148, v94, v95
	v_cvt_pk_bf16_f32 v149, v96, v97
	v_lshl_add_u64 v[94:95], v[210:211], 0, s[52:53]
	s_mov_b32 s4, m0
	s_mov_b32 m0, s5
	s_nop 0
	global_load_lds_dwordx4 v[94:95], off
	s_mov_b32 m0, s4
	v_add_f32_e32 v118, v190, v118
	s_waitcnt lgkmcnt(14)
	v_mfma_f32_32x32x16_bf16 v[18:33], v[166:169], v[212:215], v[18:33]
	v_exp_f32_e32 v98, v98
	v_exp_f32_e32 v99, v99
	v_exp_f32_e32 v100, v100
	v_exp_f32_e32 v101, v101
	s_waitcnt lgkmcnt(12)
	v_mfma_f32_32x32x16_bf16 v[34:49], v[166:169], v[114:117], v[34:49]
	v_exp_f32_e32 v102, v102
	v_exp_f32_e32 v103, v103
	v_exp_f32_e32 v104, v104
	v_exp_f32_e32 v105, v105
	ds_read_b128 v[128:131], v219 offset:8192
	ds_read_b128 v[132:135], v219 offset:8704
	s_waitcnt lgkmcnt(12)
	v_mfma_f32_32x32x16_bf16 v[18:33], v[158:161], v[138:141], v[18:33]
	v_exp_f32_e32 v106, v106
	v_exp_f32_e32 v107, v107
	v_exp_f32_e32 v108, v108
	v_exp_f32_e32 v109, v109
	ds_read_b128 v[136:139], v219 offset:10240
	ds_read_b128 v[140:143], v219 offset:10752
	s_waitcnt lgkmcnt(12)
	v_mfma_f32_32x32x16_bf16 v[34:49], v[158:161], v[120:123], v[34:49]
	v_exp_f32_e32 v110, v110
	v_exp_f32_e32 v111, v111
	v_exp_f32_e32 v112, v112
	v_exp_f32_e32 v113, v113
	ds_read_b128 v[120:123], v219 offset:12288
	ds_read_b128 v[178:181], v219 offset:12800
	s_waitcnt lgkmcnt(12)
	v_mfma_f32_32x32x16_bf16 v[18:33], v[150:153], v[124:127], v[18:33]
	v_exp_f32_e32 v66, v66
	v_exp_f32_e32 v67, v67
	v_exp_f32_e32 v68, v68
	v_exp_f32_e32 v69, v69
	ds_read_b128 v[124:127], v219 offset:14336
	ds_read_b128 v[114:117], v219 offset:14848
	s_waitcnt lgkmcnt(12)
	v_mfma_f32_32x32x16_bf16 v[34:49], v[150:153], v[82:85], v[34:49]
	v_exp_f32_e32 v70, v70
	v_exp_f32_e32 v71, v71
	v_exp_f32_e32 v72, v72
	v_exp_f32_e32 v73, v73
	s_waitcnt lgkmcnt(10)
	v_mfma_f32_32x32x16_bf16 v[18:33], v[146:149], v[86:89], v[18:33]
	v_exp_f32_e32 v74, v74
	v_exp_f32_e32 v75, v75
	v_exp_f32_e32 v76, v76
	v_exp_f32_e32 v77, v77
	s_waitcnt lgkmcnt(8)
	v_mfma_f32_32x32x16_bf16 v[34:49], v[146:149], v[90:93], v[34:49]
	v_exp_f32_e32 v78, v78
	v_exp_f32_e32 v79, v79
	v_exp_f32_e32 v80, v80
	v_exp_f32_e32 v81, v81
	s_waitcnt vmcnt(0) lgkmcnt(0)
	s_barrier
; #define WAIT_BAR(N) asm volatile("s_waitcnt vmcnt(" #N ") lgkmcnt(0)\n\ts_barrier":::"memory")
;   #define RESC() do{}while(0)
;   #define ROT() do{sl_prev=sl_cur;sl_cur=sl_next;sl_next=(sl_next==(NSLOT-1)*SLOTB)?0:sl_next+SLOTB;}while(0)
;   #define ENDW(tt) do{ if((tt)+3<NT){WAIT_BAR(2);} else if((tt)+2<NT){WAIT_BAR(1);} else {WAIT_BAR(0);} }while(0)
; template<int THRL> __device__ __forceinline__ void attn_unit(int b,int h,int qb,const bf16*Q,const bf16*__restrict__ K,const bf16*__restrict__ V,bf16*O,char*shm,float m2){
;     ...
;   int t=1;
;   for(;t+5<NT;t+=2){
;     STEP(pB0,pB1,pA0,pA1,t,true,true,true);     WAIT_BAR(2); RESC(); ROT();
;     STEP(pA0,pA1,pB0,pB1,t+1,true,true,true);   WAIT_BAR(2); RESC(); ROT();
;   }
;     ...
;   for(;t+1<NT;t+=2){
;     STEP(pB0,pB1,pA0,pA1,t,(t+3<NT),(t+1<NT),(t+1<NT));       ENDW(t);   RESC(); ROT();
;     STEP(pA0,pA1,pB0,pB1,t+1,(t+4<NT),(t+2<NT),(t+2<NT));     ENDW(t+1); RESC(); ROT();
;   }
;   STEP(pB0,pB1,pA0,pA1,NT-1,false,false,false); RESC();
	ds_read_b64_tr_b16 v[182:183], v220 offset:24576
	ds_read_b64_tr_b16 v[184:185], v220 offset:25088
	v_add_f32_e32 v82, v98, v99
	v_add_f32_e32 v82, v100, v82
	v_add_f32_e32 v82, v101, v82
	v_add_f32_e32 v82, v102, v82
	v_add_f32_e32 v119, v103, v82
	v_cvt_pk_bf16_f32 v166, v98, v99
	v_cvt_pk_bf16_f32 v167, v100, v101
	s_waitcnt lgkmcnt(9)
	v_mfma_f32_32x32x16_bf16 v[82:97], v[128:131], v[174:177], v[50:65]
	ds_read_b64_tr_b16 v[98:99], v220 offset:28672
	ds_read_b64_tr_b16 v[100:101], v220 offset:29184
	s_waitcnt lgkmcnt(10)
	v_mfma_f32_32x32x16_bf16 v[50:65], v[132:135], v[174:177], v[50:65]
	v_add_f32_e32 v119, v104, v119
	v_add_f32_e32 v119, v105, v119
	v_add_f32_e32 v119, v106, v119
	v_add_f32_e32 v119, v107, v119
	v_cvt_pk_bf16_f32 v168, v102, v103
	v_cvt_pk_bf16_f32 v169, v104, v105
	ds_read_b64_tr_b16 v[102:103], v220 offset:25600
	ds_read_b64_tr_b16 v[104:105], v220 offset:26112
	v_add_f32_e32 v119, v108, v119
	v_add_f32_e32 v119, v109, v119
	v_add_f32_e32 v119, v110, v119
	v_add_f32_e32 v119, v111, v119
	v_cvt_pk_bf16_f32 v158, v106, v107
	v_cvt_pk_bf16_f32 v159, v108, v109
	s_waitcnt lgkmcnt(11)
	v_mfma_f32_32x32x16_bf16 v[82:97], v[136:139], v[170:173], v[82:97]
	ds_read_b64_tr_b16 v[106:107], v220 offset:29696
	ds_read_b64_tr_b16 v[108:109], v220 offset:30208
	s_waitcnt lgkmcnt(12)
	v_mfma_f32_32x32x16_bf16 v[50:65], v[140:143], v[170:173], v[50:65]
	v_add_f32_e32 v119, v112, v119
	v_add_f32_e32 v119, v113, v119
	v_add_f32_e32 v119, v66, v119
	v_add_f32_e32 v119, v67, v119
	v_cvt_pk_bf16_f32 v160, v110, v111
	v_cvt_pk_bf16_f32 v161, v112, v113
	ds_read_b64_tr_b16 v[110:111], v220 offset:26624
	ds_read_b64_tr_b16 v[112:113], v220 offset:27136
	v_add_f32_e32 v119, v68, v119
	v_add_f32_e32 v119, v69, v119
	v_add_f32_e32 v119, v70, v119
	v_add_f32_e32 v119, v71, v119
	v_cvt_pk_bf16_f32 v150, v66, v67
	v_cvt_pk_bf16_f32 v151, v68, v69
	s_waitcnt lgkmcnt(13)
	v_mfma_f32_32x32x16_bf16 v[82:97], v[120:123], v[162:165], v[82:97]
	ds_read_b64_tr_b16 v[66:67], v220 offset:30720
	ds_read_b64_tr_b16 v[68:69], v220 offset:31232
	s_waitcnt lgkmcnt(14)
	v_mfma_f32_32x32x16_bf16 v[50:65], v[178:181], v[162:165], v[50:65]
	v_add_f32_e32 v119, v72, v119
	v_add_f32_e32 v119, v73, v119
	v_add_f32_e32 v119, v74, v119
	v_add_f32_e32 v119, v75, v119
	v_cvt_pk_bf16_f32 v152, v70, v71
	v_cvt_pk_bf16_f32 v153, v72, v73
	ds_read_b64_tr_b16 v[70:71], v220 offset:27648
	ds_read_b64_tr_b16 v[72:73], v220 offset:28160
	v_add_f32_e32 v119, v76, v119
	v_add_f32_e32 v119, v77, v119
	v_add_f32_e32 v119, v78, v119
	v_add_f32_e32 v119, v79, v119
	v_cvt_pk_bf16_f32 v146, v74, v75
	v_cvt_pk_bf16_f32 v147, v76, v77
	s_waitcnt lgkmcnt(14)
	v_mfma_f32_32x32x16_bf16 v[82:97], v[124:127], v[154:157], v[82:97]
	ds_read_b64_tr_b16 v[74:75], v220 offset:31744
	ds_read_b64_tr_b16 v[76:77], v220 offset:32256
	v_mfma_f32_32x32x16_bf16 v[50:65], v[114:117], v[154:157], v[50:65]
	v_add_f32_e32 v114, v80, v119
	v_add_f32_e32 v114, v81, v114
	v_add_f32_e32 v114, 0, v114
	v_cvt_pk_bf16_f32 v148, v78, v79
	v_cvt_pk_bf16_f32 v149, v80, v81
	s_waitcnt lgkmcnt(14)
	v_mfma_f32_32x32x16_bf16 v[18:33], v[166:169], v[182:185], v[18:33]
	s_nop 1
	v_exp_f32_e32 v82, v82
	v_exp_f32_e32 v83, v83
	v_exp_f32_e32 v84, v84
	v_exp_f32_e32 v85, v85
	s_waitcnt lgkmcnt(12)
	v_mfma_f32_32x32x16_bf16 v[34:49], v[166:169], v[98:101], v[34:49]
	v_exp_f32_e32 v86, v86
	v_exp_f32_e32 v87, v87
	v_exp_f32_e32 v88, v88
	v_exp_f32_e32 v89, v89
	s_waitcnt lgkmcnt(10)
	v_mfma_f32_32x32x16_bf16 v[18:33], v[158:161], v[102:105], v[18:33]
	v_exp_f32_e32 v90, v90
	v_exp_f32_e32 v91, v91
	v_exp_f32_e32 v92, v92
	v_exp_f32_e32 v93, v93
	s_waitcnt lgkmcnt(8)
	v_mfma_f32_32x32x16_bf16 v[34:49], v[158:161], v[106:109], v[34:49]
	v_exp_f32_e32 v94, v94
	v_exp_f32_e32 v95, v95
	v_exp_f32_e32 v96, v96
	v_exp_f32_e32 v97, v97
	s_waitcnt lgkmcnt(6)
; #define SBAR() __builtin_amdgcn_sched_barrier(0)
;   #define PKW(P,B) cvtpk_s(P[B],P[B+1])
; template<int THRL> __device__ __forceinline__ void attn_unit(int b,int h,int qb,const bf16*Q,const bf16*__restrict__ K,const bf16*__restrict__ V,bf16*O,char*shm,float m2){
;     ...
;   { float sacc=pB0[0]+pB0[1]; _Pragma("unroll") for(int r=2;r<16;++r)sacc+=pB0[r]; _Pragma("unroll") for(int r=0;r<16;++r)sacc+=pB1[r]; l_reg+=sacc;
;     pw0=(u32x4){PKW(pB0,0),PKW(pB0,2),PKW(pB0,4),PKW(pB0,6)};pw1=(u32x4){PKW(pB0,8),PKW(pB0,10),PKW(pB0,12),PKW(pB0,14)};pw2=(u32x4){PKW(pB1,0),PKW(pB1,2),PKW(pB1,4),PKW(pB1,6)};pw3=(u32x4){PKW(pB1,8),PKW(pB1,10),PKW(pB1,12),PKW(pB1,14)};
;     SBAR(); pv(o,vb0+sl_cur,PAF(0),PAF(1),PAF(2),PAF(3)); }
;     ...
;   {auto rr=__builtin_amdgcn_permlane32_swap(__float_as_uint(l_reg),__float_as_uint(l_reg),false,false);l_reg=__uint_as_float(rr[0])+__uint_as_float(rr[1]);}
;   if(hi==0)wsf[32+r32]=l_reg;asm volatile("s_waitcnt lgkmcnt(0)":::"memory");
	v_mfma_f32_32x32x16_bf16 v[18:33], v[150:153], v[110:113], v[18:33]
	v_exp_f32_e32 v50, v50
	v_exp_f32_e32 v51, v51
	v_exp_f32_e32 v52, v52
	v_exp_f32_e32 v53, v53
	s_waitcnt lgkmcnt(4)
	v_mfma_f32_32x32x16_bf16 v[34:49], v[150:153], v[66:69], v[34:49]
	v_exp_f32_e32 v54, v54
	v_exp_f32_e32 v55, v55
	v_exp_f32_e32 v56, v56
	v_exp_f32_e32 v57, v57
	s_waitcnt lgkmcnt(2)
	v_mfma_f32_32x32x16_bf16 v[18:33], v[146:149], v[70:73], v[18:33]
	v_exp_f32_e32 v58, v58
	v_exp_f32_e32 v59, v59
	v_exp_f32_e32 v60, v60
	v_exp_f32_e32 v61, v61
	s_waitcnt lgkmcnt(0)
	v_mfma_f32_32x32x16_bf16 v[34:49], v[146:149], v[74:77], v[34:49]
	v_exp_f32_e32 v62, v62
	v_exp_f32_e32 v63, v63
	v_exp_f32_e32 v64, v64
	v_exp_f32_e32 v65, v65
	v_add_f32_e32 v66, v82, v83
	v_add_f32_e32 v66, v84, v66
	v_add_f32_e32 v66, v85, v66
	v_add_f32_e32 v66, v86, v66
	v_add_f32_e32 v66, v87, v66
	v_add_f32_e32 v66, v88, v66
	v_add_f32_e32 v66, v89, v66
	v_add_f32_e32 v66, v90, v66
	v_add_f32_e32 v66, v91, v66
	v_add_f32_e32 v66, v92, v66
	v_add_f32_e32 v66, v93, v66
	v_add_f32_e32 v66, v94, v66
	v_add_f32_e32 v66, v95, v66
	v_add_f32_e32 v66, v96, v66
	v_add_f32_e32 v66, v97, v66
	v_add_f32_e32 v66, v50, v66
	v_add_f32_e32 v66, v51, v66
	v_add_f32_e32 v66, v52, v66
	v_add_f32_e32 v66, v53, v66
	v_add_f32_e32 v66, v54, v66
	v_add_f32_e32 v66, v55, v66
	v_add_f32_e32 v66, v56, v66
	v_add_f32_e32 v66, v57, v66
	v_add_f32_e32 v66, v58, v66
	v_add_f32_e32 v66, v59, v66
	v_add_f32_e32 v66, v60, v66
	v_add_f32_e32 v66, v61, v66
	v_add_f32_e32 v66, v62, v66
	v_add_f32_e32 v66, v63, v66
	v_add_f32_e32 v66, v64, v66
	v_add_f32_e32 v66, v65, v66
	v_add_f32_e32 v67, v118, v114
	v_add_f32_e32 v66, v67, v66
	v_cvt_pk_bf16_f32 v50, v50, v51
	v_cvt_pk_bf16_f32 v68, v82, v83
	v_cvt_pk_bf16_f32 v69, v84, v85
	v_cvt_pk_bf16_f32 v70, v86, v87
	v_cvt_pk_bf16_f32 v71, v88, v89
	v_cvt_pk_bf16_f32 v72, v90, v91
	v_cvt_pk_bf16_f32 v73, v92, v93
	v_cvt_pk_bf16_f32 v74, v94, v95
	v_cvt_pk_bf16_f32 v75, v96, v97
	v_cvt_pk_bf16_f32 v51, v52, v53
	v_cvt_pk_bf16_f32 v52, v54, v55
	v_cvt_pk_bf16_f32 v53, v56, v57
	v_cvt_pk_bf16_f32 v54, v58, v59
	v_cvt_pk_bf16_f32 v55, v60, v61
	v_cvt_pk_bf16_f32 v56, v62, v63
	v_cvt_pk_bf16_f32 v57, v64, v65
	ds_read_b64_tr_b16 v[58:59],v221 offset:0
	ds_read_b64_tr_b16 v[60:61],v221 offset:512
	ds_read_b64_tr_b16 v[62:63],v221 offset:1024
	ds_read_b64_tr_b16 v[64:65],v221 offset:1536
	ds_read_b64_tr_b16 v[76:77],v221 offset:2048
	ds_read_b64_tr_b16 v[78:79],v221 offset:2560
	ds_read_b64_tr_b16 v[80:81],v221 offset:3072
	ds_read_b64_tr_b16 v[82:83],v221 offset:3584
	s_waitcnt lgkmcnt(0)
	s_nop 0
	v_mfma_f32_32x32x16_bf16 v[18:33], v[68:71], v[58:61], v[18:33]
	ds_read_b64_tr_b16 v[58:59],v221 offset:4096
	ds_read_b64_tr_b16 v[60:61],v221 offset:4608
	v_mfma_f32_32x32x16_bf16 v[18:33], v[72:75], v[62:65], v[18:33]
	ds_read_b64_tr_b16 v[62:63],v221 offset:5120
	ds_read_b64_tr_b16 v[64:65],v221 offset:5632
	v_mfma_f32_32x32x16_bf16 v[18:33], v[50:53], v[76:79], v[18:33]
	ds_read_b64_tr_b16 v[76:77],v221 offset:6144
	ds_read_b64_tr_b16 v[78:79],v221 offset:6656
	v_mfma_f32_32x32x16_bf16 v[18:33], v[54:57], v[80:83], v[18:33]
	ds_read_b64_tr_b16 v[80:81],v221 offset:7168
	ds_read_b64_tr_b16 v[82:83],v221 offset:7680
	s_waitcnt lgkmcnt(0)
	v_mfma_f32_32x32x16_bf16 v[34:49], v[68:71], v[58:61], v[34:49]
	v_mfma_f32_32x32x16_bf16 v[34:49], v[72:75], v[62:65], v[34:49]
	v_mfma_f32_32x32x16_bf16 v[34:49], v[50:53], v[76:79], v[34:49]
	v_mov_b32_e32 v50, v66
	s_nop 1
	v_permlane32_swap_b32_e32 v66, v50
	v_mfma_f32_32x32x16_bf16 v[34:49], v[54:57], v[80:83], v[34:49]
	s_and_saveexec_b64 s[4:5], s[2:3]
	s_cbranch_execz .LBB0_823
	v_add_f32_e32 v50, v66, v50
	v_lshl_add_u32 v51, v1, 2, s0
	ds_write_b32 v51, v50 offset:49280
	s_branch .LBB0_823
